# v019_rot2
# baseline (speedup 1.0000x reference)
; __device__ __forceinline__ void phase_mixers(const Params& p, int cidx, int layer) {
;     ...
; #pragma unroll 1
;   for (;;) {
;     const int tidx = opaque_tid();
;     const int wid = tidx >> 6;
;     __syncthreads();
;     if (tidx == 0) s_item = atomicAdd(ctr, 1);
;     __syncthreads();
;     const int it = s_item;
;     if (it >= N_SSM + N_POOL + N_ATT + n_cv) break;
;     if (it < N_SSM) ssm_item(p, layer, it & 127, tidx);
;     else if (it < N_SSM + N_POOL) pool_block_item(p, layer, (it - N_SSM) & 255, tidx);
;     else if (it < N_SSM + N_POOL + N_ATT) attn_wave_item(p, ((it - N_SSM - N_POOL) & 511) * 8 + wid, tidx);
;     else cv_item_B(p, (it - N_SSM - N_POOL - N_ATT) % CV_B, tidx);
.LBB0_77:
	s_or_b64 exec, exec, s[6:7]
	s_waitcnt lgkmcnt(0)
	s_barrier
	ds_read_b32 v0, v163 offset:20
	s_mov_b64 s[6:7], -1
	s_waitcnt lgkmcnt(0)
	v_cmp_le_i32_e32 vcc, s65, v0
	v_readfirstlane_b32 s64, v0
	s_cbranch_vccnz .LBB0_72
	v_ashrrev_i32_e32 v97, 6, v164
	s_cmp_eq_u32 s65, 0x624
	s_cbranch_scc0 .Lrot_done
	s_cmp_lt_u32 s64, 0x80
	s_cbranch_scc1 .Lrot_done
	s_cmp_lt_u32 s64, 0x324
	s_cbranch_scc1 .Lrot_cv
	s_sub_u32 s64, s64, 0x2a4
	s_branch .Lrot_done
.Lrot_cv:
	s_add_u32 s64, s64, 0x300
